# weight-conversion phase: per-workgroup tile counts balanced further (two of the four 128-tile transposes moved to the other half of the workgroups)
# speedup vs baseline: 1.0030x; 1.0030x over previous
; template <int NW>
; DEV void convT(LAS unsigned char* lds, const float* src, int K, int Nsrc, bf16_t* dst, int Npad, int mode, int rot) {
;     ...
;     int tix = (blockIdx.x + G - (rot % G)) % G;
;     float ld[NL];
;     if (tix < ntiles) { const int n0 = (tix / ntk) * NW, k0 = (tix % ntk) * 64; const int sc = map_col(n0 + n, Nsrc, mode);
.LBB0_499:
	s_or_b64 exec, exec, s[4:5]
	v_cvt_f32_u32_e32 v0, s71
	s_load_dwordx2 s[4:5], s[0:1], 0x18
	s_mul_i32 s7, s14, 0x2a30000
	s_mul_hi_i32 s6, s14, 0x2a30000
	v_rcp_iflag_f32_e32 v0, v0
	s_waitcnt vmcnt(0)
	v_mov_b32_e32 v20, v210
	s_waitcnt lgkmcnt(0)
	s_add_u32 s4, s4, s7
	s_addc_u32 s5, s5, s6
	v_mul_f32_e32 v0, 0x4f7ffffe, v0
	v_cvt_u32_f32_e32 v0, v0
	s_sub_i32 s6, 0, s71
	s_add_i32 s12, s71, s2
	v_readfirstlane_b32 s13, v0
	s_mul_i32 s6, s6, s13
	s_mul_hi_u32 s6, s13, s6
	s_add_i32 s13, s13, s6
	s_mul_hi_u32 s6, s12, s13
	s_mul_i32 s6, s6, s71
	s_sub_i32 s6, s12, s6
	s_sub_i32 s7, s6, s71
	s_cmp_ge_u32 s6, s71
	s_cselect_b32 s6, s7, s6
	s_waitcnt vmcnt(0)
	v_ashrrev_i32_e32 v24, 31, v20
	s_sub_i32 s7, s6, s71
	v_lshrrev_b32_e32 v2, 25, v24
	s_cmp_ge_u32 s6, s71
	v_add_u32_e32 v2, v20, v2
	s_cselect_b32 s20, s7, s6
	v_ashrrev_i32_e32 v21, 7, v2
	v_and_b32_e32 v2, 0xffffff80, v2
	s_add_i32 s20, s20, 0xa0

; template <int NW>
; DEV void convT(LAS unsigned char* lds, const float* src, int K, int Nsrc, bf16_t* dst, int Npad, int mode, int rot) {
;     ...
;     int tix = (blockIdx.x + G - (rot % G)) % G;
.LBB0_752:
	s_add_i32 s21, s21, 0x80

; template <int NW>
; DEV void convT(LAS unsigned char* lds, const float* src, int K, int Nsrc, bf16_t* dst, int Npad, int mode, int rot) {
;     ...
;     int tix = (blockIdx.x + G - (rot % G)) % G;
;     float ld[NL];
;     if (tix < ntiles) { const int n0 = (tix / ntk) * NW, k0 = (tix % ntk) * 64; const int sc = map_col(n0 + n, Nsrc, mode);
; #pragma unroll
;         for (int i = 0; i < NL; ++i) ld[i] = sc >= 0 ? __builtin_nontemporal_load(src + (size_t)(k0 + i * RPI + kr) * Nsrc + sc) : 0.f; }
.Lrot_wbr_ok:
	s_cmpk_lt_i32 s21, 0x80
	s_cselect_b64 s[40:41], 0, -1
	s_load_dwordx2 s[4:5], s[0:1], 0x70
	v_mov_b32_e32 v23, v210
	s_waitcnt lgkmcnt(0)
	s_add_u32 s4, s4, s44
	v_ashrrev_i32_e32 v25, 31, v23
	v_lshrrev_b32_e32 v0, 25, v25
	v_add_u32_e32 v0, v23, v0
	v_ashrrev_i32_e32 v22, 7, v0
	v_and_b32_e32 v0, 0xffffff80, v0
	s_addc_u32 s5, s5, s45
	s_and_b64 vcc, exec, s[40:41]
	v_sub_u32_e32 v24, v23, v0
	s_cbranch_vccnz .LBB0_786
	s_ashr_i32 s6, s21, 31
	s_lshr_b32 s6, s6, 28
	s_add_i32 s6, s21, s6
	s_lshl_b32 s7, s6, 3
	s_and_b32 s6, s6, 0x3fffff0
	s_and_b32 s7, s7, 0xffffff80
	s_sub_i32 s6, s21, s6
	v_add_u32_e32 v0, s7, v24
	v_lshl_add_u32 v18, s6, 6, v22
	v_cmp_lt_i32_e64 s[42:43], -1, v0
	v_lshl_add_u64 v[20:21], v[0:1], 2, s[4:5]
	s_waitcnt vmcnt(0)
	v_mov_b32_e32 v3, 0
	v_ashrrev_i32_e32 v19, 31, v18
	v_mov_b32_e32 v2, 0
	s_and_saveexec_b64 s[6:7], s[42:43]
	s_cbranch_execz .LBB0_755
	v_lshlrev_b64 v[4:5], 12, v[18:19]
	v_lshl_add_u64 v[4:5], v[20:21], 0, v[4:5]
	global_load_dword v2, v[4:5], off nt
